# attention: the five next-tile pointer increments moved from the end-of-tile staging block into the mandatory wait slot between the last QK MFMA and the first VALU read of its result (s_nop 11 -> 5 VAL
# speedup vs baseline: 1.0022x; 1.0022x over previous
; #define LAS __attribute__((address_space(3)))
; __device__ __forceinline__ int crow(int r, int hi) { return (r & 3) + 8 * (r >> 2) + 4 * hi; }
; #define MFMA32(a, b, c) __builtin_amdgcn_mfma_f32_32x32x16_bf16((a), (b), (c), 0, 0, 0)
; __device__ __forceinline__ void unit(LAS unsigned char* lds, const Tensors& T, int h, int qrow0, int nact, bool sample, int limbase, int kv0, int kvnew, int nt) {
;     ...
;     for (int t = 0; t < nt; ++t) {
;         const int buf = t & 1;
;         if (t + 1 < nt) ATT_ISSUE(t + 1);
;         if (active && t <= lim) {
;             const LAS unsigned char* kp = lds + OFF_K + buf * KBUF + r32 * KP + hi * 16;
;             f32x16 p0, p1;
; #pragma unroll
;             for (int r = 0; r < 16; ++r) { p0[r] = 0.f; p1[r] = 0.f; }
;             { bf16x8 kf[4][2];
; #pragma unroll
;               for (int i = 0; i < 4; ++i) { kf[i][0] = *(const LAS bf16x8*)(kp + i * 32); kf[i][1] = *(const LAS bf16x8*)(kp + 32 * KP + i * 32); }
;               __builtin_amdgcn_sched_barrier(0);
; #pragma unroll
;               for (int i = 0; i < 12; ++i) {
;                   p0 = MFMA32(kf[i & 3][0], qf[i], p0); p1 = MFMA32(kf[i & 3][1], qf[i], p1);
;                   if (i + 4 < 12) { kf[i & 3][0] = *(const LAS bf16x8*)(kp + (i + 4) * 32); kf[i & 3][1] = *(const LAS bf16x8*)(kp + 32 * KP + (i + 4) * 32); }
;                   __builtin_amdgcn_sched_barrier(0);
;               } }
;             float rm = fmaxf(p0[0], p1[0]);
; #pragma unroll
;             for (int r = 1; r < 16; ++r) rm = fmaxf(rm, fmaxf(p0[r], p1[r]));
;             { const auto rr = __builtin_amdgcn_permlane32_swap(__float_as_uint(rm), __float_as_uint(rm), false, false);
;               rm = fmaxf(__uint_as_float(rr[0]), __uint_as_float(rr[1])); }
;             const bool need = rm > mrun + 8.0f;
;             if (__builtin_amdgcn_ballot_w64(need) != 0ull) {
;                 const float mn = need ? rm : mrun; const float alpha = __builtin_amdgcn_exp2f(mrun - mn); mrun = mn; lrun *= alpha;
;                 if (hi == 0) scr[r32] = alpha;
;                 asm volatile("s_waitcnt lgkmcnt(0)" ::: "memory");
; #pragma unroll
;                 for (int r = 0; r < 16; ++r) { const float f = scr[crow(r, hi)];
; #pragma unroll
;                     for (int d = 0; d < 4; ++d) o[d][r] *= f; }
;                 asm volatile("s_waitcnt lgkmcnt(0)" ::: "memory");
;             }
.Lat_prio:
.LBB0_904:
	s_and_b32 s16, s9, 1
	s_cmp_gt_i32 s9, s10
	s_cselect_b64 s[0:1], -1, 0
	s_or_b64 s[0:1], s[22:23], s[0:1]
	s_and_b64 vcc, exec, s[0:1]
	s_cbranch_vccnz .LBB0_909
	s_mul_i32 s0, s16, 0x6400
	v_add_u32_e32 v222, s0, v221
	ds_read_b128 v[64:67], v222
	ds_read_b128 v[224:227], v222 offset:32
	ds_read_b128 v[68:71], v222 offset:12800
	ds_read_b128 v[228:231], v222 offset:12832
	ds_read_b128 v[232:235], v222 offset:64
	ds_read_b128 v[236:239], v222 offset:96
	ds_read_b128 v[240:243], v222 offset:12864
	ds_read_b128 v[244:247], v222 offset:12896
	global_load_dwordx4 v[160:163], v[198:199], off
	global_load_dwordx4 v[156:159], v[194:195], off
	global_load_dwordx4 v[152:155], v[192:193], off
	global_load_dwordx4 v[148:151], v[204:205], off
	global_load_dwordx4 v[144:147], v[202:203], off
	s_waitcnt lgkmcnt(7)
	v_mfma_f32_32x32x16_bf16 v[80:95], v[64:67], v[140:143], 0
	ds_read_b128 v[248:251], v222 offset:128
	ds_read_b128 v[166:169], v222 offset:12928
	s_waitcnt lgkmcnt(7)
	v_mfma_f32_32x32x16_bf16 v[64:79], v[68:71], v[140:143], 0
	v_mfma_f32_32x32x16_bf16 v[80:95], v[224:227], v[136:139], v[80:95]
	s_waitcnt lgkmcnt(6)
	v_mfma_f32_32x32x16_bf16 v[64:79], v[228:231], v[136:139], v[64:79]
	ds_read_b128 v[224:227], v222 offset:160
	ds_read_b128 v[228:231], v222 offset:12960
	s_waitcnt lgkmcnt(7)
	v_mfma_f32_32x32x16_bf16 v[80:95], v[232:235], v[132:135], v[80:95]
	s_waitcnt lgkmcnt(5)
	v_mfma_f32_32x32x16_bf16 v[64:79], v[240:243], v[132:135], v[64:79]
	ds_read_b128 v[232:235], v222 offset:192
	ds_read_b128 v[240:243], v222 offset:12992
	v_mfma_f32_32x32x16_bf16 v[80:95], v[236:239], v[128:131], v[80:95]
	s_waitcnt lgkmcnt(6)
	v_mfma_f32_32x32x16_bf16 v[64:79], v[244:247], v[128:131], v[64:79]
	ds_read_b128 v[236:239], v222 offset:224
	ds_read_b128 v[244:247], v222 offset:13024
	s_waitcnt lgkmcnt(7)
	v_mfma_f32_32x32x16_bf16 v[80:95], v[248:251], v[124:127], v[80:95]
	s_waitcnt lgkmcnt(6)
	v_mfma_f32_32x32x16_bf16 v[64:79], v[166:169], v[124:127], v[64:79]
	ds_read_b128 v[166:169], v222 offset:256
	ds_read_b128 v[248:251], v222 offset:13056
	s_waitcnt lgkmcnt(7)
	v_mfma_f32_32x32x16_bf16 v[80:95], v[224:227], v[120:123], v[80:95]
	s_waitcnt lgkmcnt(6)
	v_mfma_f32_32x32x16_bf16 v[64:79], v[228:231], v[120:123], v[64:79]
	ds_read_b128 v[224:227], v222 offset:288
	ds_read_b128 v[228:231], v222 offset:13088
	s_waitcnt lgkmcnt(7)
	v_mfma_f32_32x32x16_bf16 v[80:95], v[232:235], v[116:119], v[80:95]
	s_waitcnt lgkmcnt(6)
	v_mfma_f32_32x32x16_bf16 v[64:79], v[240:243], v[116:119], v[64:79]
	ds_read_b128 v[232:235], v222 offset:320
	ds_read_b128 v[240:243], v222 offset:13120
	s_waitcnt lgkmcnt(7)
	v_mfma_f32_32x32x16_bf16 v[80:95], v[236:239], v[112:115], v[80:95]
	s_waitcnt lgkmcnt(6)
	v_mfma_f32_32x32x16_bf16 v[64:79], v[244:247], v[112:115], v[64:79]
	ds_read_b128 v[236:239], v222 offset:352
	ds_read_b128 v[244:247], v222 offset:13152
	s_waitcnt lgkmcnt(7)
	v_mfma_f32_32x32x16_bf16 v[80:95], v[166:169], v[108:111], v[80:95]
	s_waitcnt lgkmcnt(6)
	v_mfma_f32_32x32x16_bf16 v[64:79], v[248:251], v[108:111], v[64:79]
	s_waitcnt lgkmcnt(5)
	v_mfma_f32_32x32x16_bf16 v[80:95], v[224:227], v[104:107], v[80:95]
	s_waitcnt lgkmcnt(4)
	v_mfma_f32_32x32x16_bf16 v[64:79], v[228:231], v[104:107], v[64:79]
	s_waitcnt lgkmcnt(3)
	v_mfma_f32_32x32x16_bf16 v[80:95], v[232:235], v[100:103], v[80:95]
	s_waitcnt lgkmcnt(2)
	v_mfma_f32_32x32x16_bf16 v[64:79], v[240:243], v[100:103], v[64:79]
	s_waitcnt lgkmcnt(1)
	v_mfma_f32_32x32x16_bf16 v[80:95], v[236:239], v[96:99], v[80:95]
	s_waitcnt lgkmcnt(0)
	v_mfma_f32_32x32x16_bf16 v[64:79], v[244:247], v[96:99], v[64:79]
	v_lshl_add_u64 v[192:193], v[192:193], 0, v[164:165]
	v_lshl_add_u64 v[194:195], v[194:195], 0, v[196:197]
	v_lshl_add_u64 v[198:199], v[198:199], 0, v[200:201]
	v_lshl_add_u64 v[202:203], v[202:203], 0, s[14:15]
	v_lshl_add_u64 v[204:205], v[204:205], 0, s[14:15]
	s_nop 6
	v_max3_f32 v224, v64, v65, v66
	v_max3_f32 v225, v67, v68, v69
	v_max3_f32 v226, v70, v71, v72
	v_max3_f32 v227, v73, v74, v75
	v_max3_f32 v228, v76, v77, v78
	v_max3_f32 v229, v79, v80, v81
	v_max3_f32 v230, v82, v83, v84
	v_max3_f32 v231, v85, v86, v87
	v_max3_f32 v232, v88, v89, v90
	v_max3_f32 v233, v91, v92, v93
	v_max3_f32 v224, v224, v225, v226
	v_max3_f32 v227, v227, v228, v229
	v_max3_f32 v230, v230, v231, v232
	v_max3_f32 v233, v233, v94, v95
	v_max3_f32 v224, v224, v227, v230
	v_max_f32_e32 v166, v224, v233
	v_mov_b32_e32 v167, v166
	s_nop 1
	v_permlane32_swap_b32_e32 v166, v167
	v_max_f32_e32 v222, v166, v167
	v_add_f32_e32 v166, 0x41000000, v223
	v_cmp_gt_f32_e32 vcc, v222, v166
	s_cbranch_vccz .LBB0_910
	s_nop 0
	v_cndmask_b32_e32 v222, v223, v222, vcc
	v_sub_f32_e32 v166, v223, v222
	v_exp_f32_e32 v223, v166
	s_and_saveexec_b64 s[0:1], s[38:39]
	ds_write_b32 v189, v223
	s_or_b64 exec, exec, s[0:1]
	v_mul_f32_e32 v191, v191, v223
	s_waitcnt lgkmcnt(0)
	v_add_u32_e32 v223, s12, v186
	ds_read_b128 v[166:169], v223
	ds_read_b128 v[224:227], v223 offset:32
	ds_read_b128 v[228:231], v223 offset:64
	ds_read_b128 v[232:235], v223 offset:96
	s_waitcnt lgkmcnt(0)
	s_waitcnt lgkmcnt(3)
	v_pk_mul_f32 v[2:3], v[2:3], v[168:169]
	s_waitcnt lgkmcnt(2)
	v_pk_mul_f32 v[4:5], v[4:5], v[224:225]
	s_waitcnt lgkmcnt(1)
	v_pk_mul_f32 v[8:9], v[8:9], v[228:229]
	s_waitcnt lgkmcnt(0)
	v_pk_mul_f32 v[12:13], v[12:13], v[232:233]
	v_pk_mul_f32 v[14:15], v[14:15], v[234:235]
	v_pk_mul_f32 v[10:11], v[10:11], v[230:231]
	v_pk_mul_f32 v[6:7], v[6:7], v[226:227]
	v_pk_mul_f32 v[0:1], v[0:1], v[166:167]
	v_pk_mul_f32 v[60:61], v[60:61], v[232:233]
	v_pk_mul_f32 v[56:57], v[56:57], v[228:229]
	v_pk_mul_f32 v[52:53], v[52:53], v[224:225]
	v_pk_mul_f32 v[62:63], v[62:63], v[234:235]
	v_pk_mul_f32 v[58:59], v[58:59], v[230:231]
	v_pk_mul_f32 v[54:55], v[54:55], v[226:227]
	v_pk_mul_f32 v[50:51], v[50:51], v[168:169]
	v_pk_mul_f32 v[48:49], v[48:49], v[166:167]
	v_pk_mul_f32 v[44:45], v[44:45], v[232:233]
	v_pk_mul_f32 v[40:41], v[40:41], v[228:229]
	v_pk_mul_f32 v[36:37], v[36:37], v[224:225]
	v_pk_mul_f32 v[46:47], v[46:47], v[234:235]
	v_pk_mul_f32 v[42:43], v[42:43], v[230:231]
	v_pk_mul_f32 v[38:39], v[38:39], v[226:227]
	v_pk_mul_f32 v[34:35], v[34:35], v[168:169]
	v_pk_mul_f32 v[32:33], v[32:33], v[166:167]
	v_pk_mul_f32 v[28:29], v[28:29], v[232:233]
	v_pk_mul_f32 v[24:25], v[24:25], v[228:229]
	v_pk_mul_f32 v[20:21], v[20:21], v[224:225]
	v_pk_mul_f32 v[30:31], v[30:31], v[234:235]
	v_pk_mul_f32 v[26:27], v[26:27], v[230:231]
	v_pk_mul_f32 v[22:23], v[22:23], v[226:227]
	v_pk_mul_f32 v[18:19], v[18:19], v[168:169]
	v_pk_mul_f32 v[16:17], v[16:17], v[166:167]
	s_branch .LBB0_911
; #define ATT_ISSUE(t) do { const int trow_ = (sample && (t) == 32) ? kvnew : kv0 + 64 * (t); \
;         _Pragma("unroll") for (int i_ = 0; i_ < 3; ++i_) kreg[i_] = *(const GAS u32x4*)(kb[i_] + (size_t)trow_ * ks[i_]); \
;         _Pragma("unroll") for (int i_ = 0; i_ < 2; ++i_) vreg[i_] = *(const GAS u32x4*)(vb[i_] + (size_t)trow_ * 2); } while (0)
; __device__ __forceinline__ void unit(LAS unsigned char* lds, const Tensors& T, int h, int qrow0, int nact, bool sample, int limbase, int kv0, int kvnew, int nt) {
;     ...
;         if (t + 1 < nt) ATT_ISSUE(t + 1);
;         if (active && t <= lim) {
.LBB0_909:
	global_load_dwordx4 v[160:163], v[198:199], off
	global_load_dwordx4 v[156:159], v[194:195], off
	global_load_dwordx4 v[152:155], v[192:193], off
	global_load_dwordx4 v[148:151], v[204:205], off
	global_load_dwordx4 v[144:147], v[202:203], off
	v_lshl_add_u64 v[192:193], v[192:193], 0, v[164:165]
	v_lshl_add_u64 v[194:195], v[194:195], 0, v[196:197]
	v_lshl_add_u64 v[198:199], v[198:199], 0, v[200:201]
	v_lshl_add_u64 v[202:203], v[202:203], 0, s[14:15]
	v_lshl_add_u64 v[204:205], v[204:205], 0, s[14:15]
	v_mov_b32_e32 v222, v223
	s_branch .LBB0_912

; #define ATT_WRITE(buf) do { _Pragma("unroll") for (int i_ = 0; i_ < 3; ++i_) *(LAS u32x4*)(lds + OFF_K + (buf) * KBUF + kd[i_]) = kreg[i_]; \
;         _Pragma("unroll") for (int i_ = 0; i_ < 2; ++i_) { LAS u32x2* d_ = (LAS u32x2*)(lds + OFF_V + (buf) * VBUF + vd[i_]); d_[0] = (u32x2){vreg[i_].x, vreg[i_].y}; d_[2] = (u32x2){vreg[i_].z, vreg[i_].w}; } } while (0)
; __device__ __forceinline__ void unit(LAS unsigned char* lds, const Tensors& T, int h, int qrow0, int nact, bool sample, int limbase, int kv0, int kvnew, int nt) {
;     ...
;         if (t + 1 < nt) ATT_WRITE(buf ^ 1);
;         __syncthreads();
.LBB0_912:
	s_xor_b32 s0, s16, 1
	s_mul_i32 s1, s0, 0x6400
	s_add_i32 s1, s1, 0
	v_add_u32_e32 v64, s1, v219
	s_waitcnt vmcnt(4)
	ds_write_b128 v64, v[160:163]
	v_add_u32_e32 v64, s1, v218
	s_mulk_i32 s0, 0xe400
	s_waitcnt vmcnt(3)
	ds_write_b128 v64, v[156:159]
	v_add_u32_e32 v64, s1, v220
	s_add_i32 s1, s1, s0
	s_waitcnt vmcnt(2)
	ds_write_b128 v64, v[152:155]
	v_add_u32_e32 v64, s1, v188
	v_add_u32_e32 v64, 0xc800, v64
	s_add_i32 s9, s9, 1
	s_waitcnt vmcnt(1)
	ds_write2_b64 v64, v[148:149], v[150:151] offset1:2
	v_add_u32_e32 v64, s1, v190
	v_add_u32_e32 v64, 0xc800, v64
	s_cmp_eq_u32 s13, s9
	s_waitcnt vmcnt(0)
	ds_write2_b64 v64, v[144:145], v[146:147] offset1:2
	s_waitcnt lgkmcnt(0)
	s_barrier
	s_cbranch_scc1 .LBB0_914
	v_mov_b32_e32 v223, v222
	s_branch .LBB0_904
